# v30: GU epilogue two-pair interleave with pk_add in blocks 1-7 (block 1 uses a freed block-0 pair; row scales packed two per pair)
# baseline (speedup 1.0000x reference)
; #define PG8_LAS __attribute__((address_space(3)))
; __device__ __forceinline__ u32x4 pack8(const f32x4 a, const f32x4 b) { u32x4 w; w.x = cvt_pk_bf16(a[0], a[1]); w.y = cvt_pk_bf16(a[2], a[3]); w.z = cvt_pk_bf16(b[0], b[1]); w.w = cvt_pk_bf16(b[2], b[3]); return w; }
;     __device__ __forceinline__ void operator()(const f32x4 (&acc)[2][2][4][2], const Unit& u, int wr, int wc, int fr, int fq) const {
;         PG8_LAS const float* R = stage_rstd((const float*)(ws + WS_PS), lds, u.pm);
; #pragma unroll
;         for (int ai = 0; ai < 2; ++ai)
; #pragma unroll
;             for (int m = 0; m < 4; ++m) {
;                 const int row = u.pm * BM + ai * HALF + wr * 64 + m * 16 + fr;
;                 const float rs = R[ai * HALF + wr * 64 + m * 16 + fr];
;                 bf16_t* ACT = (bf16_t*)(ws + WS_ACT);
;                 f32x4 a[2];
; #pragma unroll
;                 for (int n = 0; n < 2; ++n) {
;                     const f32x4 g = acc[ai][0][m][n] * rs, uu = acc[ai][1][m][n] * rs;
; #pragma unroll
;                     for (int j = 0; j < 4; ++j) a[n][j] = g[j] * __builtin_amdgcn_rcpf(1.0f + __builtin_amdgcn_exp2f(-1.4426950408889634f * g[j])) * uu[j];
;                 }
;                 *(u32x4*)(ACT + (size_t)row * 2816 + u.pn * 128 + wc * 32 + 8 * fq) = pack8(a[0], a[1]);
;             }
.LBB0_38:
	s_lshl_b32 s3, s48, 8
	ds_read_b32 v146, v142
	v_mov_b32_e32 v145, 0xbfb8aa3b
	s_waitcnt lgkmcnt(0)
	v_pk_mul_f32 v[124:125], v[124:125], v[146:147] op_sel_hi:[1,0]
	v_pk_mul_f32 v[126:127], v[126:127], v[146:147] op_sel_hi:[1,0]
	v_pk_mul_f32 v[116:117], v[116:117], v[146:147] op_sel_hi:[1,0]
	v_pk_mul_f32 v[118:119], v[118:119], v[146:147] op_sel_hi:[1,0]
	v_pk_mul_f32 v[120:121], v[120:121], v[146:147] op_sel_hi:[1,0]
	v_pk_mul_f32 v[122:123], v[122:123], v[146:147] op_sel_hi:[1,0]
	v_pk_mul_f32 v[112:113], v[112:113], v[146:147] op_sel_hi:[1,0]
	v_pk_mul_f32 v[114:115], v[114:115], v[146:147] op_sel_hi:[1,0]
	v_pk_mul_f32 v[148:149], v[124:125], v[144:145] op_sel:[0,1] op_sel_hi:[1,1]
	v_exp_f32_e32 v148, v148
	v_exp_f32_e32 v149, v149
	v_add_f32_e32 v148, 1.0, v148
	v_add_f32_e32 v149, 1.0, v149
	v_rcp_f32_e32 v148, v148
	v_rcp_f32_e32 v149, v149
	s_nop 0
	v_pk_mul_f32 v[124:125], v[124:125], v[148:149]
	v_pk_mul_f32 v[120:121], v[120:121], v[124:125]
	v_pk_mul_f32 v[148:149], v[126:127], v[144:145] op_sel:[0,1] op_sel_hi:[1,1]
	v_exp_f32_e32 v148, v148
	v_exp_f32_e32 v149, v149
	v_add_f32_e32 v148, 1.0, v148
	v_add_f32_e32 v149, 1.0, v149
	v_rcp_f32_e32 v148, v148
	v_rcp_f32_e32 v149, v149
	s_nop 0
	v_pk_mul_f32 v[126:127], v[126:127], v[148:149]
	v_pk_mul_f32 v[122:123], v[122:123], v[126:127]
	v_pk_mul_f32 v[148:149], v[116:117], v[144:145] op_sel:[0,1] op_sel_hi:[1,1]
	v_exp_f32_e32 v148, v148
	v_exp_f32_e32 v149, v149
	v_add_f32_e32 v148, 1.0, v148
	v_add_f32_e32 v149, 1.0, v149
	v_rcp_f32_e32 v148, v148
	v_rcp_f32_e32 v149, v149
	s_nop 0
	v_pk_mul_f32 v[116:117], v[116:117], v[148:149]
	v_pk_mul_f32 v[112:113], v[112:113], v[116:117]
	v_pk_mul_f32 v[148:149], v[118:119], v[144:145] op_sel:[0,1] op_sel_hi:[1,1]
	v_exp_f32_e32 v148, v148
	v_exp_f32_e32 v149, v149
	v_add_f32_e32 v148, 1.0, v148
	v_add_f32_e32 v149, 1.0, v149
	v_rcp_f32_e32 v148, v148
	v_rcp_f32_e32 v149, v149
	s_nop 0
	v_pk_mul_f32 v[118:119], v[118:119], v[148:149]
	v_pk_mul_f32 v[114:115], v[114:115], v[118:119]
	v_cvt_pk_bf16_f32 v116, v112, v113
	v_cvt_pk_bf16_f32 v117, v114, v115
	v_cvt_pk_bf16_f32 v114, v120, v121
	v_cvt_pk_bf16_f32 v115, v122, v123
	s_lshl_b32 s0, s47, 7
	v_add_u32_e32 v144, s3, v140
	s_ashr_i32 s1, s0, 31
	s_movk_i32 s3, 0x1600
	s_lshl_b64 s[0:1], s[0:1], 1
	s_andn2_b64 vcc, exec, s[36:37]
	v_mov_b64_e32 v[112:113], s[16:17]
	s_mov_b32 s101, 0
	v_mad_i64_i32 v[118:119], s[4:5], v144, s3, v[112:113]
	v_lshl_add_u64 v[118:119], v[118:119], 0, s[0:1]
	v_lshl_add_u64 v[118:119], v[118:119], 0, s[34:35]
	v_lshl_add_u64 v[118:119], v[118:119], 0, v[184:185]
	global_store_dwordx4 v[118:119], v[114:117], off
	ds_read_b32 v114, v142 offset:64
	ds_read_b32 v120, v142 offset:128
	ds_read_b32 v121, v142 offset:192
	ds_read_b32 v122, v142 offset:512
	ds_read_b32 v123, v142 offset:576
	ds_read_b32 v124, v142 offset:640
	ds_read_b32 v125, v142 offset:704
	v_mov_b32_e32 v116, 1.0
	s_waitcnt lgkmcnt(6)
	v_pk_mul_f32 v[108:109], v[108:109], v[114:115] op_sel_hi:[1,0]
	v_pk_mul_f32 v[110:111], v[110:111], v[114:115] op_sel_hi:[1,0]
	v_pk_mul_f32 v[100:101], v[100:101], v[114:115] op_sel_hi:[1,0]
	v_pk_mul_f32 v[102:103], v[102:103], v[114:115] op_sel_hi:[1,0]
	v_pk_mul_f32 v[104:105], v[104:105], v[114:115] op_sel_hi:[1,0]
	v_pk_mul_f32 v[106:107], v[106:107], v[114:115] op_sel_hi:[1,0]
	v_pk_mul_f32 v[96:97], v[96:97], v[114:115] op_sel_hi:[1,0]
	v_pk_mul_f32 v[98:99], v[98:99], v[114:115] op_sel_hi:[1,0]
	v_pk_mul_f32 v[148:149], v[108:109], v[144:145] op_sel:[0,1] op_sel_hi:[1,1]
	v_pk_mul_f32 v[126:127], v[110:111], v[144:145] op_sel:[0,1] op_sel_hi:[1,1]
	v_exp_f32_e32 v148, v148
	v_exp_f32_e32 v149, v149
	v_exp_f32_e32 v126, v126
	v_exp_f32_e32 v127, v127
	v_pk_add_f32 v[148:149], v[148:149], v[116:117] op_sel_hi:[1,0]
	v_pk_add_f32 v[126:127], v[126:127], v[116:117] op_sel_hi:[1,0]
	v_rcp_f32_e32 v148, v148
	v_rcp_f32_e32 v149, v149
	v_rcp_f32_e32 v126, v126
	v_rcp_f32_e32 v127, v127
	v_pk_mul_f32 v[108:109], v[108:109], v[148:149]
	v_pk_mul_f32 v[110:111], v[110:111], v[126:127]
	v_pk_mul_f32 v[104:105], v[104:105], v[108:109]
	v_pk_mul_f32 v[106:107], v[106:107], v[110:111]
	v_pk_mul_f32 v[148:149], v[100:101], v[144:145] op_sel:[0,1] op_sel_hi:[1,1]
	v_pk_mul_f32 v[126:127], v[102:103], v[144:145] op_sel:[0,1] op_sel_hi:[1,1]
	v_exp_f32_e32 v148, v148
	v_exp_f32_e32 v149, v149
	v_exp_f32_e32 v126, v126
	v_exp_f32_e32 v127, v127
	v_pk_add_f32 v[148:149], v[148:149], v[116:117] op_sel_hi:[1,0]
	v_pk_add_f32 v[126:127], v[126:127], v[116:117] op_sel_hi:[1,0]
	v_rcp_f32_e32 v148, v148
	v_rcp_f32_e32 v149, v149
	v_rcp_f32_e32 v126, v126
	v_rcp_f32_e32 v127, v127
	v_pk_mul_f32 v[100:101], v[100:101], v[148:149]
	v_pk_mul_f32 v[102:103], v[102:103], v[126:127]
	v_pk_mul_f32 v[96:97], v[96:97], v[100:101]
	v_pk_mul_f32 v[98:99], v[98:99], v[102:103]
	v_cvt_pk_bf16_f32 v99, v98, v99
	v_cvt_pk_bf16_f32 v98, v96, v97
	v_cvt_pk_bf16_f32 v96, v104, v105
	v_cvt_pk_bf16_f32 v97, v106, v107
	s_mov_b32 s100, 0x16000
	v_lshl_add_u64 v[100:101], v[118:119], 0, s[100:101]
	global_store_dwordx4 v[100:101], v[96:99], off
	s_waitcnt lgkmcnt(0)
; __device__ __forceinline__ u32x4 pack8(const f32x4 a, const f32x4 b) { u32x4 w; w.x = cvt_pk_bf16(a[0], a[1]); w.y = cvt_pk_bf16(a[2], a[3]); w.z = cvt_pk_bf16(b[0], b[1]); w.w = cvt_pk_bf16(b[2], b[3]); return w; }
;     __device__ __forceinline__ void operator()(const f32x4 (&acc)[2][2][4][2], const Unit& u, int wr, int wc, int fr, int fq) const {
;     ...
;             for (int m = 0; m < 4; ++m) {
;                 const int row = u.pm * BM + ai * HALF + wr * 64 + m * 16 + fr;
;                 const float rs = R[ai * HALF + wr * 64 + m * 16 + fr];
;                 bf16_t* ACT = (bf16_t*)(ws + WS_ACT);
;                 f32x4 a[2];
; #pragma unroll
;                 for (int n = 0; n < 2; ++n) {
;                     const f32x4 g = acc[ai][0][m][n] * rs, uu = acc[ai][1][m][n] * rs;
; #pragma unroll
;                     for (int j = 0; j < 4; ++j) a[n][j] = g[j] * __builtin_amdgcn_rcpf(1.0f + __builtin_amdgcn_exp2f(-1.4426950408889634f * g[j])) * uu[j];
;                 }
;                 *(u32x4*)(ACT + (size_t)row * 2816 + u.pn * 128 + wc * 32 + 8 * fq) = pack8(a[0], a[1]);
;             }
	v_pk_mul_f32 v[92:93], v[92:93], v[120:121] op_sel_hi:[1,0]
	v_pk_mul_f32 v[94:95], v[94:95], v[120:121] op_sel_hi:[1,0]
	v_pk_mul_f32 v[84:85], v[84:85], v[120:121] op_sel_hi:[1,0]
	v_pk_mul_f32 v[86:87], v[86:87], v[120:121] op_sel_hi:[1,0]
	v_pk_mul_f32 v[88:89], v[88:89], v[120:121] op_sel_hi:[1,0]
	v_pk_mul_f32 v[90:91], v[90:91], v[120:121] op_sel_hi:[1,0]
	v_pk_mul_f32 v[80:81], v[80:81], v[120:121] op_sel_hi:[1,0]
	v_pk_mul_f32 v[82:83], v[82:83], v[120:121] op_sel_hi:[1,0]
	v_pk_mul_f32 v[148:149], v[92:93], v[144:145] op_sel:[0,1] op_sel_hi:[1,1]
	v_pk_mul_f32 v[114:115], v[94:95], v[144:145] op_sel:[0,1] op_sel_hi:[1,1]
	v_exp_f32_e32 v148, v148
	v_exp_f32_e32 v149, v149
	v_exp_f32_e32 v114, v114
	v_exp_f32_e32 v115, v115
	v_pk_add_f32 v[148:149], v[148:149], v[116:117] op_sel_hi:[1,0]
	v_pk_add_f32 v[114:115], v[114:115], v[116:117] op_sel_hi:[1,0]
	v_rcp_f32_e32 v148, v148
	v_rcp_f32_e32 v149, v149
	v_rcp_f32_e32 v114, v114
	v_rcp_f32_e32 v115, v115
	v_pk_mul_f32 v[92:93], v[92:93], v[148:149]
	v_pk_mul_f32 v[94:95], v[94:95], v[114:115]
	v_pk_mul_f32 v[88:89], v[88:89], v[92:93]
	v_pk_mul_f32 v[90:91], v[90:91], v[94:95]
	v_pk_mul_f32 v[148:149], v[84:85], v[144:145] op_sel:[0,1] op_sel_hi:[1,1]
	v_pk_mul_f32 v[114:115], v[86:87], v[144:145] op_sel:[0,1] op_sel_hi:[1,1]
	v_exp_f32_e32 v148, v148
	v_exp_f32_e32 v149, v149
	v_exp_f32_e32 v114, v114
	v_exp_f32_e32 v115, v115
	v_pk_add_f32 v[148:149], v[148:149], v[116:117] op_sel_hi:[1,0]
	v_pk_add_f32 v[114:115], v[114:115], v[116:117] op_sel_hi:[1,0]
	v_rcp_f32_e32 v148, v148
	v_rcp_f32_e32 v149, v149
	v_rcp_f32_e32 v114, v114
	v_rcp_f32_e32 v115, v115
	v_pk_mul_f32 v[84:85], v[84:85], v[148:149]
	v_pk_mul_f32 v[86:87], v[86:87], v[114:115]
	v_pk_mul_f32 v[80:81], v[80:81], v[84:85]
	v_pk_mul_f32 v[82:83], v[82:83], v[86:87]
	v_cvt_pk_bf16_f32 v83, v82, v83
	v_cvt_pk_bf16_f32 v82, v80, v81
	v_cvt_pk_bf16_f32 v80, v88, v89
	v_cvt_pk_bf16_f32 v81, v90, v91
	s_mov_b32 s100, 0x2c000
	v_lshl_add_u64 v[84:85], v[118:119], 0, s[100:101]
	global_store_dwordx4 v[84:85], v[80:83], off
	s_waitcnt lgkmcnt(0)
	v_pk_mul_f32 v[76:77], v[76:77], v[120:121] op_sel:[0,1] op_sel_hi:[1,1]
	v_pk_mul_f32 v[78:79], v[78:79], v[120:121] op_sel:[0,1] op_sel_hi:[1,1]
	v_pk_mul_f32 v[68:69], v[68:69], v[120:121] op_sel:[0,1] op_sel_hi:[1,1]
	v_pk_mul_f32 v[70:71], v[70:71], v[120:121] op_sel:[0,1] op_sel_hi:[1,1]
	v_pk_mul_f32 v[72:73], v[72:73], v[120:121] op_sel:[0,1] op_sel_hi:[1,1]
	v_pk_mul_f32 v[74:75], v[74:75], v[120:121] op_sel:[0,1] op_sel_hi:[1,1]
	v_pk_mul_f32 v[64:65], v[64:65], v[120:121] op_sel:[0,1] op_sel_hi:[1,1]
	v_pk_mul_f32 v[66:67], v[66:67], v[120:121] op_sel:[0,1] op_sel_hi:[1,1]
	v_pk_mul_f32 v[148:149], v[76:77], v[144:145] op_sel:[0,1] op_sel_hi:[1,1]
	v_pk_mul_f32 v[114:115], v[78:79], v[144:145] op_sel:[0,1] op_sel_hi:[1,1]
	v_exp_f32_e32 v148, v148
	v_exp_f32_e32 v149, v149
	v_exp_f32_e32 v114, v114
	v_exp_f32_e32 v115, v115
	v_pk_add_f32 v[148:149], v[148:149], v[116:117] op_sel_hi:[1,0]
	v_pk_add_f32 v[114:115], v[114:115], v[116:117] op_sel_hi:[1,0]
	v_rcp_f32_e32 v148, v148
	v_rcp_f32_e32 v149, v149
	v_rcp_f32_e32 v114, v114
	v_rcp_f32_e32 v115, v115
	v_pk_mul_f32 v[76:77], v[76:77], v[148:149]
	v_pk_mul_f32 v[78:79], v[78:79], v[114:115]
	v_pk_mul_f32 v[72:73], v[72:73], v[76:77]
	v_pk_mul_f32 v[74:75], v[74:75], v[78:79]
	v_pk_mul_f32 v[148:149], v[68:69], v[144:145] op_sel:[0,1] op_sel_hi:[1,1]
	v_pk_mul_f32 v[114:115], v[70:71], v[144:145] op_sel:[0,1] op_sel_hi:[1,1]
	v_exp_f32_e32 v148, v148
	v_exp_f32_e32 v149, v149
	v_exp_f32_e32 v114, v114
	v_exp_f32_e32 v115, v115
	v_pk_add_f32 v[148:149], v[148:149], v[116:117] op_sel_hi:[1,0]
	v_pk_add_f32 v[114:115], v[114:115], v[116:117] op_sel_hi:[1,0]
	v_rcp_f32_e32 v148, v148
	v_rcp_f32_e32 v149, v149
	v_rcp_f32_e32 v114, v114
	v_rcp_f32_e32 v115, v115
	v_pk_mul_f32 v[68:69], v[68:69], v[148:149]
	v_pk_mul_f32 v[70:71], v[70:71], v[114:115]
	v_pk_mul_f32 v[64:65], v[64:65], v[68:69]
	v_pk_mul_f32 v[66:67], v[66:67], v[70:71]
	v_cvt_pk_bf16_f32 v67, v66, v67
	v_cvt_pk_bf16_f32 v66, v64, v65
	v_cvt_pk_bf16_f32 v64, v72, v73
	v_cvt_pk_bf16_f32 v65, v74, v75
	s_mov_b32 s100, 0x42000
	v_lshl_add_u64 v[68:69], v[118:119], 0, s[100:101]
	global_store_dwordx4 v[68:69], v[64:67], off
	s_waitcnt lgkmcnt(0)
	v_pk_mul_f32 v[60:61], v[60:61], v[122:123] op_sel_hi:[1,0]
	v_pk_mul_f32 v[62:63], v[62:63], v[122:123] op_sel_hi:[1,0]
	v_pk_mul_f32 v[52:53], v[52:53], v[122:123] op_sel_hi:[1,0]
	v_pk_mul_f32 v[54:55], v[54:55], v[122:123] op_sel_hi:[1,0]
	v_pk_mul_f32 v[56:57], v[56:57], v[122:123] op_sel_hi:[1,0]
	v_pk_mul_f32 v[58:59], v[58:59], v[122:123] op_sel_hi:[1,0]
	v_pk_mul_f32 v[48:49], v[48:49], v[122:123] op_sel_hi:[1,0]
	v_pk_mul_f32 v[50:51], v[50:51], v[122:123] op_sel_hi:[1,0]
	v_pk_mul_f32 v[148:149], v[60:61], v[144:145] op_sel:[0,1] op_sel_hi:[1,1]
	v_pk_mul_f32 v[114:115], v[62:63], v[144:145] op_sel:[0,1] op_sel_hi:[1,1]
	v_exp_f32_e32 v148, v148
	v_exp_f32_e32 v149, v149
	v_exp_f32_e32 v114, v114
	v_exp_f32_e32 v115, v115
	v_pk_add_f32 v[148:149], v[148:149], v[116:117] op_sel_hi:[1,0]
	v_pk_add_f32 v[114:115], v[114:115], v[116:117] op_sel_hi:[1,0]
	v_rcp_f32_e32 v148, v148
	v_rcp_f32_e32 v149, v149
	v_rcp_f32_e32 v114, v114
	v_rcp_f32_e32 v115, v115
	v_pk_mul_f32 v[60:61], v[60:61], v[148:149]
	v_pk_mul_f32 v[62:63], v[62:63], v[114:115]
	v_pk_mul_f32 v[56:57], v[56:57], v[60:61]
	v_pk_mul_f32 v[58:59], v[58:59], v[62:63]
	v_pk_mul_f32 v[148:149], v[52:53], v[144:145] op_sel:[0,1] op_sel_hi:[1,1]
	v_pk_mul_f32 v[114:115], v[54:55], v[144:145] op_sel:[0,1] op_sel_hi:[1,1]
	v_exp_f32_e32 v148, v148
	v_exp_f32_e32 v149, v149
	v_exp_f32_e32 v114, v114
	v_exp_f32_e32 v115, v115
	v_pk_add_f32 v[148:149], v[148:149], v[116:117] op_sel_hi:[1,0]
	v_pk_add_f32 v[114:115], v[114:115], v[116:117] op_sel_hi:[1,0]
	v_rcp_f32_e32 v148, v148
	v_rcp_f32_e32 v149, v149
	v_rcp_f32_e32 v114, v114
	v_rcp_f32_e32 v115, v115
	v_pk_mul_f32 v[52:53], v[52:53], v[148:149]
	v_pk_mul_f32 v[54:55], v[54:55], v[114:115]
	v_pk_mul_f32 v[48:49], v[48:49], v[52:53]
	v_pk_mul_f32 v[50:51], v[50:51], v[54:55]
	v_cvt_pk_bf16_f32 v51, v50, v51
	v_cvt_pk_bf16_f32 v50, v48, v49
	v_cvt_pk_bf16_f32 v48, v56, v57
	v_cvt_pk_bf16_f32 v49, v58, v59
	s_mov_b32 s100, 0xb0000
	v_lshl_add_u64 v[52:53], v[118:119], 0, s[100:101]
	global_store_dwordx4 v[52:53], v[48:51], off
	s_waitcnt lgkmcnt(0)
; __device__ __forceinline__ u32x4 pack8(const f32x4 a, const f32x4 b) { u32x4 w; w.x = cvt_pk_bf16(a[0], a[1]); w.y = cvt_pk_bf16(a[2], a[3]); w.z = cvt_pk_bf16(b[0], b[1]); w.w = cvt_pk_bf16(b[2], b[3]); return w; }
;     __device__ __forceinline__ void operator()(const f32x4 (&acc)[2][2][4][2], const Unit& u, int wr, int wc, int fr, int fq) const {
;     ...
;             for (int m = 0; m < 4; ++m) {
;                 const int row = u.pm * BM + ai * HALF + wr * 64 + m * 16 + fr;
;                 const float rs = R[ai * HALF + wr * 64 + m * 16 + fr];
;                 bf16_t* ACT = (bf16_t*)(ws + WS_ACT);
;                 f32x4 a[2];
; #pragma unroll
;                 for (int n = 0; n < 2; ++n) {
;                     const f32x4 g = acc[ai][0][m][n] * rs, uu = acc[ai][1][m][n] * rs;
; #pragma unroll
;                     for (int j = 0; j < 4; ++j) a[n][j] = g[j] * __builtin_amdgcn_rcpf(1.0f + __builtin_amdgcn_exp2f(-1.4426950408889634f * g[j])) * uu[j];
;                 }
;                 *(u32x4*)(ACT + (size_t)row * 2816 + u.pn * 128 + wc * 32 + 8 * fq) = pack8(a[0], a[1]);
;             }
	v_pk_mul_f32 v[44:45], v[44:45], v[122:123] op_sel:[0,1] op_sel_hi:[1,1]
	v_pk_mul_f32 v[46:47], v[46:47], v[122:123] op_sel:[0,1] op_sel_hi:[1,1]
	v_pk_mul_f32 v[36:37], v[36:37], v[122:123] op_sel:[0,1] op_sel_hi:[1,1]
	v_pk_mul_f32 v[38:39], v[38:39], v[122:123] op_sel:[0,1] op_sel_hi:[1,1]
	v_pk_mul_f32 v[40:41], v[40:41], v[122:123] op_sel:[0,1] op_sel_hi:[1,1]
	v_pk_mul_f32 v[42:43], v[42:43], v[122:123] op_sel:[0,1] op_sel_hi:[1,1]
	v_pk_mul_f32 v[32:33], v[32:33], v[122:123] op_sel:[0,1] op_sel_hi:[1,1]
	v_pk_mul_f32 v[34:35], v[34:35], v[122:123] op_sel:[0,1] op_sel_hi:[1,1]
	v_pk_mul_f32 v[148:149], v[44:45], v[144:145] op_sel:[0,1] op_sel_hi:[1,1]
	v_pk_mul_f32 v[114:115], v[46:47], v[144:145] op_sel:[0,1] op_sel_hi:[1,1]
	v_exp_f32_e32 v148, v148
	v_exp_f32_e32 v149, v149
	v_exp_f32_e32 v114, v114
	v_exp_f32_e32 v115, v115
	v_pk_add_f32 v[148:149], v[148:149], v[116:117] op_sel_hi:[1,0]
	v_pk_add_f32 v[114:115], v[114:115], v[116:117] op_sel_hi:[1,0]
	v_rcp_f32_e32 v148, v148
	v_rcp_f32_e32 v149, v149
	v_rcp_f32_e32 v114, v114
	v_rcp_f32_e32 v115, v115
	v_pk_mul_f32 v[44:45], v[44:45], v[148:149]
	v_pk_mul_f32 v[46:47], v[46:47], v[114:115]
	v_pk_mul_f32 v[40:41], v[40:41], v[44:45]
	v_pk_mul_f32 v[42:43], v[42:43], v[46:47]
	v_pk_mul_f32 v[148:149], v[36:37], v[144:145] op_sel:[0,1] op_sel_hi:[1,1]
	v_pk_mul_f32 v[114:115], v[38:39], v[144:145] op_sel:[0,1] op_sel_hi:[1,1]
	v_exp_f32_e32 v148, v148
	v_exp_f32_e32 v149, v149
	v_exp_f32_e32 v114, v114
	v_exp_f32_e32 v115, v115
	v_pk_add_f32 v[148:149], v[148:149], v[116:117] op_sel_hi:[1,0]
	v_pk_add_f32 v[114:115], v[114:115], v[116:117] op_sel_hi:[1,0]
	v_rcp_f32_e32 v148, v148
	v_rcp_f32_e32 v149, v149
	v_rcp_f32_e32 v114, v114
	v_rcp_f32_e32 v115, v115
	v_pk_mul_f32 v[36:37], v[36:37], v[148:149]
	v_pk_mul_f32 v[38:39], v[38:39], v[114:115]
	v_pk_mul_f32 v[32:33], v[32:33], v[36:37]
	v_pk_mul_f32 v[34:35], v[34:35], v[38:39]
	v_cvt_pk_bf16_f32 v35, v34, v35
	v_cvt_pk_bf16_f32 v34, v32, v33
	v_cvt_pk_bf16_f32 v32, v40, v41
	v_cvt_pk_bf16_f32 v33, v42, v43
	s_mov_b32 s100, 0xc6000
	v_lshl_add_u64 v[36:37], v[118:119], 0, s[100:101]
	global_store_dwordx4 v[36:37], v[32:35], off
	s_waitcnt lgkmcnt(0)
	v_pk_mul_f32 v[28:29], v[28:29], v[124:125] op_sel_hi:[1,0]
	v_pk_mul_f32 v[30:31], v[30:31], v[124:125] op_sel_hi:[1,0]
	v_pk_mul_f32 v[20:21], v[20:21], v[124:125] op_sel_hi:[1,0]
	v_pk_mul_f32 v[22:23], v[22:23], v[124:125] op_sel_hi:[1,0]
	v_pk_mul_f32 v[24:25], v[24:25], v[124:125] op_sel_hi:[1,0]
	v_pk_mul_f32 v[26:27], v[26:27], v[124:125] op_sel_hi:[1,0]
	v_pk_mul_f32 v[16:17], v[16:17], v[124:125] op_sel_hi:[1,0]
	v_pk_mul_f32 v[18:19], v[18:19], v[124:125] op_sel_hi:[1,0]
	v_pk_mul_f32 v[148:149], v[28:29], v[144:145] op_sel:[0,1] op_sel_hi:[1,1]
	v_pk_mul_f32 v[114:115], v[30:31], v[144:145] op_sel:[0,1] op_sel_hi:[1,1]
	v_exp_f32_e32 v148, v148
	v_exp_f32_e32 v149, v149
	v_exp_f32_e32 v114, v114
	v_exp_f32_e32 v115, v115
	v_pk_add_f32 v[148:149], v[148:149], v[116:117] op_sel_hi:[1,0]
	v_pk_add_f32 v[114:115], v[114:115], v[116:117] op_sel_hi:[1,0]
	v_rcp_f32_e32 v148, v148
	v_rcp_f32_e32 v149, v149
	v_rcp_f32_e32 v114, v114
	v_rcp_f32_e32 v115, v115
	v_pk_mul_f32 v[28:29], v[28:29], v[148:149]
	v_pk_mul_f32 v[30:31], v[30:31], v[114:115]
	v_pk_mul_f32 v[24:25], v[24:25], v[28:29]
	v_pk_mul_f32 v[26:27], v[26:27], v[30:31]
	v_pk_mul_f32 v[148:149], v[20:21], v[144:145] op_sel:[0,1] op_sel_hi:[1,1]
	v_pk_mul_f32 v[114:115], v[22:23], v[144:145] op_sel:[0,1] op_sel_hi:[1,1]
	v_exp_f32_e32 v148, v148
	v_exp_f32_e32 v149, v149
	v_exp_f32_e32 v114, v114
	v_exp_f32_e32 v115, v115
	v_pk_add_f32 v[148:149], v[148:149], v[116:117] op_sel_hi:[1,0]
	v_pk_add_f32 v[114:115], v[114:115], v[116:117] op_sel_hi:[1,0]
	v_rcp_f32_e32 v148, v148
	v_rcp_f32_e32 v149, v149
	v_rcp_f32_e32 v114, v114
	v_rcp_f32_e32 v115, v115
	v_pk_mul_f32 v[20:21], v[20:21], v[148:149]
	v_pk_mul_f32 v[22:23], v[22:23], v[114:115]
	v_pk_mul_f32 v[16:17], v[16:17], v[20:21]
	v_pk_mul_f32 v[18:19], v[18:19], v[22:23]
	v_cvt_pk_bf16_f32 v19, v18, v19
	v_cvt_pk_bf16_f32 v18, v16, v17
	v_cvt_pk_bf16_f32 v16, v24, v25
	v_cvt_pk_bf16_f32 v17, v26, v27
	s_mov_b32 s100, 0xdc000
	v_lshl_add_u64 v[20:21], v[118:119], 0, s[100:101]
	global_store_dwordx4 v[20:21], v[16:19], off
	s_waitcnt lgkmcnt(0)
	v_pk_mul_f32 v[12:13], v[12:13], v[124:125] op_sel:[0,1] op_sel_hi:[1,1]
	v_pk_mul_f32 v[14:15], v[14:15], v[124:125] op_sel:[0,1] op_sel_hi:[1,1]
	v_pk_mul_f32 v[4:5], v[4:5], v[124:125] op_sel:[0,1] op_sel_hi:[1,1]
	v_pk_mul_f32 v[6:7], v[6:7], v[124:125] op_sel:[0,1] op_sel_hi:[1,1]
	v_pk_mul_f32 v[8:9], v[8:9], v[124:125] op_sel:[0,1] op_sel_hi:[1,1]
	v_pk_mul_f32 v[10:11], v[10:11], v[124:125] op_sel:[0,1] op_sel_hi:[1,1]
	v_pk_mul_f32 v[0:1], v[0:1], v[124:125] op_sel:[0,1] op_sel_hi:[1,1]
	v_pk_mul_f32 v[2:3], v[2:3], v[124:125] op_sel:[0,1] op_sel_hi:[1,1]
	v_pk_mul_f32 v[148:149], v[12:13], v[144:145] op_sel:[0,1] op_sel_hi:[1,1]
	v_pk_mul_f32 v[114:115], v[14:15], v[144:145] op_sel:[0,1] op_sel_hi:[1,1]
	v_exp_f32_e32 v148, v148
	v_exp_f32_e32 v149, v149
	v_exp_f32_e32 v114, v114
	v_exp_f32_e32 v115, v115
	v_pk_add_f32 v[148:149], v[148:149], v[116:117] op_sel_hi:[1,0]
	v_pk_add_f32 v[114:115], v[114:115], v[116:117] op_sel_hi:[1,0]
	v_rcp_f32_e32 v148, v148
	v_rcp_f32_e32 v149, v149
	v_rcp_f32_e32 v114, v114
	v_rcp_f32_e32 v115, v115
	v_pk_mul_f32 v[12:13], v[12:13], v[148:149]
	v_pk_mul_f32 v[14:15], v[14:15], v[114:115]
	v_pk_mul_f32 v[8:9], v[8:9], v[12:13]
	v_pk_mul_f32 v[10:11], v[10:11], v[14:15]
	v_pk_mul_f32 v[148:149], v[4:5], v[144:145] op_sel:[0,1] op_sel_hi:[1,1]
	v_pk_mul_f32 v[114:115], v[6:7], v[144:145] op_sel:[0,1] op_sel_hi:[1,1]
	v_exp_f32_e32 v148, v148
	v_exp_f32_e32 v149, v149
	v_exp_f32_e32 v114, v114
	v_exp_f32_e32 v115, v115
	v_pk_add_f32 v[148:149], v[148:149], v[116:117] op_sel_hi:[1,0]
	v_pk_add_f32 v[114:115], v[114:115], v[116:117] op_sel_hi:[1,0]
	v_rcp_f32_e32 v148, v148
	v_rcp_f32_e32 v149, v149
	v_rcp_f32_e32 v114, v114
	v_rcp_f32_e32 v115, v115
	v_pk_mul_f32 v[4:5], v[4:5], v[148:149]
	v_pk_mul_f32 v[6:7], v[6:7], v[114:115]
	v_pk_mul_f32 v[0:1], v[0:1], v[4:5]
	v_pk_mul_f32 v[2:3], v[2:3], v[6:7]
	v_cvt_pk_bf16_f32 v3, v2, v3
	v_cvt_pk_bf16_f32 v2, v0, v1
	v_cvt_pk_bf16_f32 v0, v8, v9
	v_cvt_pk_bf16_f32 v1, v10, v11
	s_mov_b32 s100, 0xf2000
	v_lshl_add_u64 v[4:5], v[118:119], 0, s[100:101]
	s_mov_b64 s[0:1], -1
	global_store_dwordx4 v[4:5], v[0:3], off
	s_cbranch_vccnz .LBB0_31
	s_andn2_b64 vcc, exec, s[8:9]
	s_cbranch_vccnz .LBB0_30
	s_barrier
	s_branch .LBB0_30
